# ffn-in: last round as 768 single 128-row tiles (3 per CU) instead of 384 paired tiles (2 on half the CUs, 1 on the rest)
# speedup vs baseline: 1.0295x; 1.0090x over previous
.LBB0_192:
	v_mov_b32_e32 v0, v1
	s_mul_hi_i32 s23, s22, 0x2e8ba2e9
	v_mbcnt_lo_u32_b32 v0, -1, v0
	v_mbcnt_hi_u32_b32 v0, -1, v0
	s_lshr_b32 s24, s23, 31
	s_ashr_i32 s23, s23, 3
	v_add_u32_e32 v90, s80, v0
	s_add_i32 s23, s23, s24
	s_cmpk_lt_u32 s22, 0x400
	s_cbranch_scc1 .Lffp_paired
	s_cmpk_eq_u32 s81, 0x200
	s_cbranch_scc0 .Lffp_paired
	s_sub_u32 s24, s22, 0x400
	s_mov_b32 s98, 0
	s_cmpk_lt_u32 s24, 0x180
	s_cbranch_scc1 .Lffs_h0
	s_sub_u32 s24, s24, 0x180
	s_mov_b32 s98, 1
.Lffs_h0:
	s_add_u32 s24, s24, 0x400
	s_mul_i32 s25, s24, 0x5d2
	s_lshr_b32 s25, s25, 16
	s_mul_i32 s23, s25, 44
	s_sub_u32 s24, s24, s23
	s_lshl_b32 s23, s25, 1
	s_or_b32 s23, s23, s98
	s_mul_i32 s20, s23, 44
	s_add_u32 s20, s20, s24
	s_lshl_b32 s20, s20, 6
	s_mov_b32 s99, s20
	s_mul_i32 s24, s23, 0xb00
	v_lshlrev_b32_e32 v0, 3, v90
	v_ashrrev_i32_e32 v89, 3, v90
	v_and_b32_e32 v88, 56, v0
	v_subrev_u32_e32 v0, s24, v89
	v_add_u32_e32 v0, s20, v0
	v_lshl_or_b32 v0, v0, 10, v88
	v_lshl_add_u64 v[72:73], v[0:1], 1, s[4:5]
	v_lshl_add_u32 v0, s23, 7, v89
	v_lshl_or_b32 v0, v0, 10, v88
	v_lshl_add_u64 v[74:75], v[0:1], 1, s[72:73]
	v_add_co_u32_e32 v76, vcc, s18, v74
	s_waitcnt lgkmcnt(0)
	s_nop 0
	v_addc_co_u32_e32 v77, vcc, 0, v75, vcc
	v_add_co_u32_e32 v78, vcc, s29, v74
	s_nop 0
	s_nop 0
	v_addc_co_u32_e32 v79, vcc, 0, v75, vcc
	v_add_co_u32_e32 v80, vcc, s10, v74
	s_nop 0
	s_nop 0
	v_addc_co_u32_e32 v81, vcc, 0, v75, vcc
	s_nop 0
	s_nop 0
	s_mov_b32 s24, 0x580000
	v_add_co_u32_e32 v82, vcc, s24, v72
	s_mov_b32 s24, 0x590000
	s_nop 0
	v_addc_co_u32_e32 v83, vcc, 0, v73, vcc
	v_add_co_u32_e32 v84, vcc, s18, v72
	s_nop 0
	s_nop 0
	v_addc_co_u32_e32 v85, vcc, 0, v73, vcc
	v_add_co_u32_e32 v86, vcc, s24, v72
	s_nop 0
	s_nop 0
	v_addc_co_u32_e32 v87, vcc, 0, v73, vcc
	s_nop 0
	v_mul_lo_u32 v34, v89, s27
	v_add_lshl_u32 v92, v34, v88, 1
	s_barrier
	v_and_b32_e32 v0, 31, v90
	v_add_u32_e32 v93, 0xd800, v92
	v_ashrrev_i32_e32 v2, 1, v90
	v_and_b32_e32 v91, 0xffffffc0, v2
	v_bfe_u32 v102, v90, 4, 3
	v_lshlrev_b32_e32 v102, 4, v102
	v_xor_b32_e32 v74, v102, v74
	v_xor_b32_e32 v76, v102, v76
	v_xor_b32_e32 v78, v102, v78
	v_xor_b32_e32 v80, v102, v80
	v_xor_b32_e32 v72, v102, v72
	v_xor_b32_e32 v82, v102, v82
	v_xor_b32_e32 v84, v102, v84
	v_xor_b32_e32 v86, v102, v86
	v_bfe_u32 v102, v90, 5, 1
	v_bfe_u32 v103, v90, 1, 3
	v_xor_b32_e32 v102, v102, v103
	v_lshlrev_b32_e32 v102, 4, v102
	v_lshrrev_b32_e32 v103, 1, v90
	v_and_b32_e32 v103, 64, v103
	v_and_b32_e32 v104, 31, v90
	v_or_b32_e32 v103, v103, v104
	v_lshl_or_b32 v94, v103, 7, v102
	v_and_b32_e32 v103, 0x5f, v90
	v_lshl_or_b32 v98, v103, 7, v102
	v_add_u32_e32 v98, 0x4000, v98
	v_xor_b32_e32 v95, 0x20, v94
	v_xor_b32_e32 v99, 0x20, v98
	v_xor_b32_e32 v96, 0x40, v94
	v_xor_b32_e32 v100, 0x40, v98
	v_xor_b32_e32 v97, 0x60, v94
	v_xor_b32_e32 v101, 0x60, v98
	v_mov_b32_e32 v214, 0x80
	v_mov_b32_e32 v215, 0
	s_lshl_b32 vcc_lo, s80, 4
	v_mov_b32_e32 v2, 0
	v_mov_b32_e32 v3, 0
	v_mov_b32_e32 v4, 0
	v_mov_b32_e32 v5, 0
	v_mov_b32_e32 v6, 0
	v_mov_b32_e32 v7, 0
	v_mov_b32_e32 v8, 0
	v_mov_b32_e32 v9, 0
	v_mov_b32_e32 v10, 0
	v_mov_b32_e32 v11, 0
	v_mov_b32_e32 v12, 0
	v_mov_b32_e32 v13, 0
	v_mov_b32_e32 v14, 0
	v_mov_b32_e32 v15, 0
	v_mov_b32_e32 v16, 0
	v_mov_b32_e32 v17, 0
	v_mov_b32_e32 v18, 0
	v_mov_b32_e32 v19, 0
	v_mov_b32_e32 v20, 0
	v_mov_b32_e32 v21, 0
	v_mov_b32_e32 v22, 0
	v_mov_b32_e32 v23, 0
	v_mov_b32_e32 v24, 0
	v_mov_b32_e32 v25, 0
	v_mov_b32_e32 v26, 0
	v_mov_b32_e32 v27, 0
	v_mov_b32_e32 v28, 0
	v_mov_b32_e32 v29, 0
	v_mov_b32_e32 v30, 0
	v_mov_b32_e32 v31, 0
	v_mov_b32_e32 v32, 0
	v_mov_b32_e32 v33, 0
	v_mov_b32_e32 v34, 0
	v_mov_b32_e32 v35, 0
	v_mov_b32_e32 v36, 0
	v_mov_b32_e32 v37, 0
	v_mov_b32_e32 v38, 0
	v_mov_b32_e32 v39, 0
	v_mov_b32_e32 v40, 0
	v_mov_b32_e32 v41, 0
	v_mov_b32_e32 v42, 0
	v_mov_b32_e32 v43, 0
	v_mov_b32_e32 v44, 0
	v_mov_b32_e32 v45, 0
	v_mov_b32_e32 v46, 0
	v_mov_b32_e32 v47, 0
	v_mov_b32_e32 v48, 0
	v_mov_b32_e32 v49, 0
	v_mov_b32_e32 v50, 0
	v_mov_b32_e32 v51, 0
	v_mov_b32_e32 v52, 0
	v_mov_b32_e32 v53, 0
	v_mov_b32_e32 v54, 0
	v_mov_b32_e32 v55, 0
	v_mov_b32_e32 v56, 0
	v_mov_b32_e32 v57, 0
	v_mov_b32_e32 v58, 0
	v_mov_b32_e32 v59, 0
	v_mov_b32_e32 v60, 0
	v_mov_b32_e32 v61, 0
	v_mov_b32_e32 v62, 0
	v_mov_b32_e32 v63, 0
	v_mov_b32_e32 v64, 0
	v_mov_b32_e32 v65, 0
	s_mov_b32 m0, vcc_lo
	s_nop 0
	global_load_lds_dwordx4 v[74:75], off
	s_add_u32 m0, vcc_lo, 0x1000
	s_nop 0
	global_load_lds_dwordx4 v[76:77], off
	s_add_u32 m0, vcc_lo, 0x2000
	s_nop 0
	global_load_lds_dwordx4 v[78:79], off
	s_add_u32 m0, vcc_lo, 0x3000
	s_nop 0
	global_load_lds_dwordx4 v[80:81], off
	s_add_u32 m0, vcc_lo, 0x4000
	s_nop 0
	global_load_lds_dwordx4 v[72:73], off
	s_add_u32 m0, vcc_lo, 0x5000
	s_nop 0
	global_load_lds_dwordx4 v[82:83], off
	s_add_u32 m0, vcc_lo, 0x6000
	s_nop 0
	global_load_lds_dwordx4 v[84:85], off
	s_add_u32 m0, vcc_lo, 0x7000
	s_nop 0
	global_load_lds_dwordx4 v[86:87], off
	v_lshl_add_u64 v[74:75], v[74:75], 0, v[214:215]
	v_lshl_add_u64 v[76:77], v[76:77], 0, v[214:215]
	v_lshl_add_u64 v[78:79], v[78:79], 0, v[214:215]
	v_lshl_add_u64 v[80:81], v[80:81], 0, v[214:215]
	v_lshl_add_u64 v[72:73], v[72:73], 0, v[214:215]
	v_lshl_add_u64 v[82:83], v[82:83], 0, v[214:215]
	v_lshl_add_u64 v[84:85], v[84:85], 0, v[214:215]
	v_lshl_add_u64 v[86:87], v[86:87], 0, v[214:215]
	s_add_u32 m0, vcc_lo, 0x8000
	s_nop 0
	global_load_lds_dwordx4 v[74:75], off
	s_add_u32 m0, vcc_lo, 0x9000
	s_nop 0
	global_load_lds_dwordx4 v[76:77], off
	s_add_u32 m0, vcc_lo, 0xa000
	s_nop 0
	global_load_lds_dwordx4 v[78:79], off
	s_add_u32 m0, vcc_lo, 0xb000
	s_nop 0
	global_load_lds_dwordx4 v[80:81], off
	s_add_u32 m0, vcc_lo, 0xc000
	s_nop 0
	global_load_lds_dwordx4 v[72:73], off
	s_add_u32 m0, vcc_lo, 0xd000
	s_nop 0
	global_load_lds_dwordx4 v[82:83], off
	s_add_u32 m0, vcc_lo, 0xe000
	s_nop 0
	global_load_lds_dwordx4 v[84:85], off
	s_add_u32 m0, vcc_lo, 0xf000
	s_nop 0
	global_load_lds_dwordx4 v[86:87], off
	v_lshl_add_u64 v[74:75], v[74:75], 0, v[214:215]
	v_lshl_add_u64 v[76:77], v[76:77], 0, v[214:215]
	v_lshl_add_u64 v[78:79], v[78:79], 0, v[214:215]
	v_lshl_add_u64 v[80:81], v[80:81], 0, v[214:215]
	v_lshl_add_u64 v[72:73], v[72:73], 0, v[214:215]
	v_lshl_add_u64 v[82:83], v[82:83], 0, v[214:215]
	v_lshl_add_u64 v[84:85], v[84:85], 0, v[214:215]
	v_lshl_add_u64 v[86:87], v[86:87], 0, v[214:215]
	s_mov_b32 vcc_hi, 7
	s_waitcnt vmcnt(8)
	s_barrier
	ds_read_b128 v[166:169], v94
	s_setprio 3
	ds_read_b128 v[170:173], v98
	ds_read_b128 v[174:177], v98 offset:4096
	ds_read_b128 v[178:181], v94 offset:4096
	ds_read_b128 v[182:185], v95
	ds_read_b128 v[188:191], v99
	ds_read_b128 v[192:195], v99 offset:4096
	ds_read_b128 v[206:209], v95 offset:4096
	s_waitcnt lgkmcnt(6)
	v_mfma_f32_32x32x16_bf16 v[34:49], v[166:169], v[170:173], v[34:49]
	ds_read_b128 v[236:239], v96
	s_waitcnt lgkmcnt(5)
	v_mfma_f32_32x32x16_bf16 v[2:17], v[178:181], v[170:173], v[2:17]
	ds_read_b128 v[240:243], v100
	v_mfma_f32_32x32x16_bf16 v[18:33], v[178:181], v[174:177], v[18:33]
	ds_read_b128 v[244:247], v100 offset:4096
	v_mfma_f32_32x32x16_bf16 v[50:65], v[166:169], v[174:177], v[50:65]
	ds_read_b128 v[248:251], v96 offset:4096
	s_waitcnt lgkmcnt(6)
	v_mfma_f32_32x32x16_bf16 v[34:49], v[182:185], v[188:191], v[34:49]
	ds_read_b128 v[126:129], v97
	s_waitcnt lgkmcnt(5)
	v_mfma_f32_32x32x16_bf16 v[2:17], v[206:209], v[188:191], v[2:17]
	ds_read_b128 v[130:133], v101
	v_mfma_f32_32x32x16_bf16 v[18:33], v[206:209], v[192:195], v[18:33]
	ds_read_b128 v[210:213], v101 offset:4096
	v_mfma_f32_32x32x16_bf16 v[50:65], v[182:185], v[192:195], v[50:65]
	ds_read_b128 v[222:225], v97 offset:4096
	s_waitcnt vmcnt(0) lgkmcnt(0)
	s_barrier
.Lg_ffs_loop:
	v_mfma_f32_32x32x16_bf16 v[34:49], v[236:239], v[240:243], v[34:49]
	s_mov_b32 m0, vcc_lo
	ds_read_b128 v[166:169], v94 offset:32768
	global_load_lds_dwordx4 v[74:75], off
	s_setprio 3
	v_mfma_f32_32x32x16_bf16 v[2:17], v[248:251], v[240:243], v[2:17]
	ds_read_b128 v[170:173], v98 offset:32768
	v_mfma_f32_32x32x16_bf16 v[18:33], v[248:251], v[244:247], v[18:33]
	s_add_u32 m0, vcc_lo, 0x1000
	ds_read_b128 v[174:177], v98 offset:36864
	global_load_lds_dwordx4 v[76:77], off
	v_mfma_f32_32x32x16_bf16 v[50:65], v[236:239], v[244:247], v[50:65]
	ds_read_b128 v[178:181], v94 offset:36864
	v_mfma_f32_32x32x16_bf16 v[34:49], v[126:129], v[130:133], v[34:49]
	s_add_u32 m0, vcc_lo, 0x2000
	ds_read_b128 v[182:185], v95 offset:32768
	global_load_lds_dwordx4 v[78:79], off
	v_mfma_f32_32x32x16_bf16 v[2:17], v[222:225], v[130:133], v[2:17]
	ds_read_b128 v[188:191], v99 offset:32768
	v_mfma_f32_32x32x16_bf16 v[18:33], v[222:225], v[210:213], v[18:33]
	s_add_u32 m0, vcc_lo, 0x3000
	ds_read_b128 v[192:195], v99 offset:36864
	global_load_lds_dwordx4 v[80:81], off
	v_mfma_f32_32x32x16_bf16 v[50:65], v[126:129], v[210:213], v[50:65]
	ds_read_b128 v[206:209], v95 offset:36864
	s_waitcnt lgkmcnt(6)
	v_mfma_f32_32x32x16_bf16 v[34:49], v[166:169], v[170:173], v[34:49]
	s_add_u32 m0, vcc_lo, 0x4000
	ds_read_b128 v[236:239], v96 offset:32768
	global_load_lds_dwordx4 v[72:73], off
	s_waitcnt lgkmcnt(5)
	v_mfma_f32_32x32x16_bf16 v[2:17], v[178:181], v[170:173], v[2:17]
	ds_read_b128 v[240:243], v100 offset:32768
	v_mfma_f32_32x32x16_bf16 v[18:33], v[178:181], v[174:177], v[18:33]
	s_add_u32 m0, vcc_lo, 0x5000
	ds_read_b128 v[244:247], v100 offset:36864
	global_load_lds_dwordx4 v[82:83], off
	v_mfma_f32_32x32x16_bf16 v[50:65], v[166:169], v[174:177], v[50:65]
	ds_read_b128 v[248:251], v96 offset:36864
	s_waitcnt lgkmcnt(6)
	v_mfma_f32_32x32x16_bf16 v[34:49], v[182:185], v[188:191], v[34:49]
	s_add_u32 m0, vcc_lo, 0x6000
	ds_read_b128 v[126:129], v97 offset:32768
	global_load_lds_dwordx4 v[84:85], off
	s_waitcnt lgkmcnt(5)
	v_mfma_f32_32x32x16_bf16 v[2:17], v[206:209], v[188:191], v[2:17]
	ds_read_b128 v[130:133], v101 offset:32768
	v_mfma_f32_32x32x16_bf16 v[18:33], v[206:209], v[192:195], v[18:33]
	s_add_u32 m0, vcc_lo, 0x7000
	ds_read_b128 v[210:213], v101 offset:36864
	global_load_lds_dwordx4 v[86:87], off
	v_mfma_f32_32x32x16_bf16 v[50:65], v[182:185], v[192:195], v[50:65]
	ds_read_b128 v[222:225], v97 offset:36864
	v_lshl_add_u64 v[74:75], v[74:75], 0, v[214:215]
	v_lshl_add_u64 v[76:77], v[76:77], 0, v[214:215]
	v_lshl_add_u64 v[78:79], v[78:79], 0, v[214:215]
	v_lshl_add_u64 v[80:81], v[80:81], 0, v[214:215]
	v_lshl_add_u64 v[72:73], v[72:73], 0, v[214:215]
	v_lshl_add_u64 v[82:83], v[82:83], 0, v[214:215]
	v_lshl_add_u64 v[84:85], v[84:85], 0, v[214:215]
	v_lshl_add_u64 v[86:87], v[86:87], 0, v[214:215]
	s_waitcnt vmcnt(0) lgkmcnt(0)
	s_barrier
	v_mfma_f32_32x32x16_bf16 v[34:49], v[236:239], v[240:243], v[34:49]
	s_add_u32 m0, vcc_lo, 0x8000
	ds_read_b128 v[166:169], v94
	global_load_lds_dwordx4 v[74:75], off
	s_setprio 3
	v_mfma_f32_32x32x16_bf16 v[2:17], v[248:251], v[240:243], v[2:17]
	ds_read_b128 v[170:173], v98
	v_mfma_f32_32x32x16_bf16 v[18:33], v[248:251], v[244:247], v[18:33]
	s_add_u32 m0, vcc_lo, 0x9000
	ds_read_b128 v[174:177], v98 offset:4096
	global_load_lds_dwordx4 v[76:77], off
	v_mfma_f32_32x32x16_bf16 v[50:65], v[236:239], v[244:247], v[50:65]
	ds_read_b128 v[178:181], v94 offset:4096
	v_mfma_f32_32x32x16_bf16 v[34:49], v[126:129], v[130:133], v[34:49]
	s_add_u32 m0, vcc_lo, 0xa000
	ds_read_b128 v[182:185], v95
	global_load_lds_dwordx4 v[78:79], off
	v_mfma_f32_32x32x16_bf16 v[2:17], v[222:225], v[130:133], v[2:17]
	ds_read_b128 v[188:191], v99
	v_mfma_f32_32x32x16_bf16 v[18:33], v[222:225], v[210:213], v[18:33]
	s_add_u32 m0, vcc_lo, 0xb000
	ds_read_b128 v[192:195], v99 offset:4096
	global_load_lds_dwordx4 v[80:81], off
	v_mfma_f32_32x32x16_bf16 v[50:65], v[126:129], v[210:213], v[50:65]
	ds_read_b128 v[206:209], v95 offset:4096
	s_waitcnt lgkmcnt(6)
	v_mfma_f32_32x32x16_bf16 v[34:49], v[166:169], v[170:173], v[34:49]
	s_add_u32 m0, vcc_lo, 0xc000
	ds_read_b128 v[236:239], v96
	global_load_lds_dwordx4 v[72:73], off
	s_waitcnt lgkmcnt(5)
	v_mfma_f32_32x32x16_bf16 v[2:17], v[178:181], v[170:173], v[2:17]
	ds_read_b128 v[240:243], v100
	v_mfma_f32_32x32x16_bf16 v[18:33], v[178:181], v[174:177], v[18:33]
	s_add_u32 m0, vcc_lo, 0xd000
	ds_read_b128 v[244:247], v100 offset:4096
	global_load_lds_dwordx4 v[82:83], off
	v_mfma_f32_32x32x16_bf16 v[50:65], v[166:169], v[174:177], v[50:65]
	ds_read_b128 v[248:251], v96 offset:4096
	s_waitcnt lgkmcnt(6)
	v_mfma_f32_32x32x16_bf16 v[34:49], v[182:185], v[188:191], v[34:49]
	s_add_u32 m0, vcc_lo, 0xe000
	ds_read_b128 v[126:129], v97
	global_load_lds_dwordx4 v[84:85], off
	s_waitcnt lgkmcnt(5)
	v_mfma_f32_32x32x16_bf16 v[2:17], v[206:209], v[188:191], v[2:17]
	ds_read_b128 v[130:133], v101
	v_mfma_f32_32x32x16_bf16 v[18:33], v[206:209], v[192:195], v[18:33]
	s_add_u32 m0, vcc_lo, 0xf000
	ds_read_b128 v[210:213], v101 offset:4096
	global_load_lds_dwordx4 v[86:87], off
	v_mfma_f32_32x32x16_bf16 v[50:65], v[182:185], v[192:195], v[50:65]
	ds_read_b128 v[222:225], v97 offset:4096
	v_lshl_add_u64 v[74:75], v[74:75], 0, v[214:215]
	v_lshl_add_u64 v[76:77], v[76:77], 0, v[214:215]
	v_lshl_add_u64 v[78:79], v[78:79], 0, v[214:215]
	v_lshl_add_u64 v[80:81], v[80:81], 0, v[214:215]
	v_lshl_add_u64 v[72:73], v[72:73], 0, v[214:215]
	v_lshl_add_u64 v[82:83], v[82:83], 0, v[214:215]
	v_lshl_add_u64 v[84:85], v[84:85], 0, v[214:215]
	v_lshl_add_u64 v[86:87], v[86:87], 0, v[214:215]
	s_waitcnt vmcnt(0) lgkmcnt(0)
	s_barrier
	s_sub_u32 vcc_hi, vcc_hi, 1
	s_cmp_lg_u32 vcc_hi, 0
	s_cbranch_scc1 .Lg_ffs_loop
	v_mfma_f32_32x32x16_bf16 v[34:49], v[236:239], v[240:243], v[34:49]
	ds_read_b128 v[166:169], v94 offset:32768
	s_setprio 3
	v_mfma_f32_32x32x16_bf16 v[2:17], v[248:251], v[240:243], v[2:17]
	ds_read_b128 v[170:173], v98 offset:32768
	v_mfma_f32_32x32x16_bf16 v[18:33], v[248:251], v[244:247], v[18:33]
	ds_read_b128 v[174:177], v98 offset:36864
	v_mfma_f32_32x32x16_bf16 v[50:65], v[236:239], v[244:247], v[50:65]
	ds_read_b128 v[178:181], v94 offset:36864
	v_mfma_f32_32x32x16_bf16 v[34:49], v[126:129], v[130:133], v[34:49]
	ds_read_b128 v[182:185], v95 offset:32768
	v_mfma_f32_32x32x16_bf16 v[2:17], v[222:225], v[130:133], v[2:17]
	ds_read_b128 v[188:191], v99 offset:32768
	v_mfma_f32_32x32x16_bf16 v[18:33], v[222:225], v[210:213], v[18:33]
	ds_read_b128 v[192:195], v99 offset:36864
	v_mfma_f32_32x32x16_bf16 v[50:65], v[126:129], v[210:213], v[50:65]
	ds_read_b128 v[206:209], v95 offset:36864
	s_waitcnt lgkmcnt(6)
	v_mfma_f32_32x32x16_bf16 v[34:49], v[166:169], v[170:173], v[34:49]
	ds_read_b128 v[236:239], v96 offset:32768
	s_waitcnt lgkmcnt(5)
	v_mfma_f32_32x32x16_bf16 v[2:17], v[178:181], v[170:173], v[2:17]
	ds_read_b128 v[240:243], v100 offset:32768
	v_mfma_f32_32x32x16_bf16 v[18:33], v[178:181], v[174:177], v[18:33]
	ds_read_b128 v[244:247], v100 offset:36864
	v_mfma_f32_32x32x16_bf16 v[50:65], v[166:169], v[174:177], v[50:65]
	ds_read_b128 v[248:251], v96 offset:36864
	s_waitcnt lgkmcnt(6)
	v_mfma_f32_32x32x16_bf16 v[34:49], v[182:185], v[188:191], v[34:49]
	ds_read_b128 v[126:129], v97 offset:32768
	s_waitcnt lgkmcnt(5)
	v_mfma_f32_32x32x16_bf16 v[2:17], v[206:209], v[188:191], v[2:17]
	ds_read_b128 v[130:133], v101 offset:32768
	v_mfma_f32_32x32x16_bf16 v[18:33], v[206:209], v[192:195], v[18:33]
	ds_read_b128 v[210:213], v101 offset:36864
	v_mfma_f32_32x32x16_bf16 v[50:65], v[182:185], v[192:195], v[50:65]
	ds_read_b128 v[222:225], v97 offset:36864
	s_waitcnt lgkmcnt(6)
	v_mfma_f32_32x32x16_bf16 v[34:49], v[236:239], v[240:243], v[34:49]
	s_waitcnt lgkmcnt(5)
	v_mfma_f32_32x32x16_bf16 v[50:65], v[236:239], v[244:247], v[50:65]
	s_waitcnt lgkmcnt(4)
	v_mfma_f32_32x32x16_bf16 v[2:17], v[248:251], v[240:243], v[2:17]
	v_mfma_f32_32x32x16_bf16 v[18:33], v[248:251], v[244:247], v[18:33]
	s_waitcnt lgkmcnt(2)
	v_mfma_f32_32x32x16_bf16 v[34:49], v[126:129], v[130:133], v[34:49]
	s_waitcnt lgkmcnt(1)
	v_mfma_f32_32x32x16_bf16 v[50:65], v[126:129], v[210:213], v[50:65]
	s_waitcnt lgkmcnt(0)
	v_mfma_f32_32x32x16_bf16 v[2:17], v[222:225], v[130:133], v[2:17]
	v_mfma_f32_32x32x16_bf16 v[18:33], v[222:225], v[210:213], v[18:33]
	s_nop 7
	s_nop 7
	s_mov_b32 m0, 0
	s_branch .Lffp_epi
.Lffp_paired:
	s_mov_b32 s98, s23
	s_mul_i32 s24, s98, 44
	s_sub_i32 s25, s22, s24
	s_mul_i32 s24, s98, 88
	s_add_i32 s24, s24, s25
	s_lshl_b32 s23, s98, 1
	s_lshl_b32 s99, s24, 6
	s_lshl_b32 s25, s25, 6
	s_lshl_b32 s24, s23, 7
	v_lshlrev_b32_e32 v0, 3, v90
	v_ashrrev_i32_e32 v89, 3, v90
	v_and_b32_e32 v88, 56, v0
	s_waitcnt lgkmcnt(0)
	v_lshrrev_b32_e32 v84, 2, v90
	v_lshrrev_b32_e32 v85, 6, v90
	v_lshl_add_u32 v84, v85, 4, v84
	v_bfe_u32 v85, v90, 4, 2
	v_and_b32_e32 v86, 3, v90
	v_xor_b32_e32 v85, v85, v86
	v_lshlrev_b32_e32 v85, 4, v85
	v_add_u32_e32 v86, s24, v84
	v_lshl_or_b32 v66, v86, 11, v85
	v_add_u32_e32 v68, 0x8000, v66
	v_add_u32_e32 v70, 0x40000, v66
	v_add_u32_e32 v72, 0x48000, v66
	s_lshr_b32 vcc_lo, s80, 6
	s_and_b32 vcc_hi, vcc_lo, 1
	s_mul_i32 vcc_hi, vcc_hi, 0xb00
	s_lshr_b32 vcc_lo, vcc_lo, 1
	s_lshl_b32 vcc_lo, vcc_lo, 5
	s_add_i32 vcc_lo, vcc_lo, vcc_hi
	s_add_i32 vcc_lo, vcc_lo, s25
	v_bfe_u32 v86, v90, 2, 4
	v_add_u32_e32 v86, vcc_lo, v86
	v_lshl_or_b32 v74, v86, 11, v85
	v_add_u32_e32 v76, 0x8000, v74
	v_mov_b32_e32 v67, 0
	v_mov_b32_e32 v69, 0
	v_mov_b32_e32 v71, 0
	v_mov_b32_e32 v73, 0
	v_mov_b32_e32 v75, 0
	v_mov_b32_e32 v77, 0
	v_lshl_add_u64 v[66:67], v[66:67], 0, s[72:73]
	v_lshl_add_u64 v[68:69], v[68:69], 0, s[72:73]
	v_lshl_add_u64 v[70:71], v[70:71], 0, s[72:73]
	v_lshl_add_u64 v[72:73], v[72:73], 0, s[72:73]
	v_lshl_add_u64 v[74:75], v[74:75], 0, s[4:5]
	v_lshl_add_u64 v[76:77], v[76:77], 0, s[4:5]
	v_mov_b32_e32 v84, 64
	v_mov_b32_e32 v85, 0
	v_lshl_add_u64 v[126:127], v[66:67], 0, v[84:85]
	v_lshl_add_u64 v[128:129], v[68:69], 0, v[84:85]
	v_lshl_add_u64 v[130:131], v[70:71], 0, v[84:85]
	v_lshl_add_u64 v[132:133], v[72:73], 0, v[84:85]
	v_lshl_add_u64 v[244:245], v[74:75], 0, v[84:85]
	v_lshl_add_u64 v[246:247], v[76:77], 0, v[84:85]
	v_bfe_u32 v84, v90, 5, 1
	v_bfe_u32 v85, v90, 2, 2
	v_xor_b32_e32 v84, v84, v85
	v_lshlrev_b32_e32 v84, 4, v84
	v_lshrrev_b32_e32 v85, 1, v90
	v_and_b32_e32 v85, 64, v85
	v_and_b32_e32 v86, 31, v90
	v_or_b32_e32 v85, v85, v86
	v_lshl_or_b32 v78, v85, 6, v84
	v_xor_b32_e32 v79, 32, v78
	v_and_b32_e32 v85, 0x5f, v90
	v_lshl_or_b32 v80, v85, 6, v84
	v_add_u32_e32 v80, 0x4000, v80
	v_xor_b32_e32 v81, 32, v80
	v_mov_b32_e32 v82, 0x80
	v_mov_b32_e32 v83, 0
	s_lshl_b32 vcc_lo, s80, 5
	v_ashrrev_i32_e32 v2, 1, v90
	v_and_b32_e32 v91, 0xffffffc0, v2
	v_and_b32_e32 v0, 31, v90
	v_mov_b32_e32 v34, 0
	v_mov_b32_e32 v35, 0
	v_mov_b32_e32 v36, 0
	v_mov_b32_e32 v37, 0
	v_mov_b32_e32 v38, 0
	v_mov_b32_e32 v39, 0
	v_mov_b32_e32 v40, 0
	v_mov_b32_e32 v41, 0
	v_mov_b32_e32 v42, 0
	v_mov_b32_e32 v43, 0
	v_mov_b32_e32 v44, 0
	v_mov_b32_e32 v45, 0
	v_mov_b32_e32 v46, 0
	v_mov_b32_e32 v47, 0
	v_mov_b32_e32 v48, 0
	v_mov_b32_e32 v49, 0
	v_mov_b32_e32 v50, 0
	v_mov_b32_e32 v51, 0
	v_mov_b32_e32 v52, 0
	v_mov_b32_e32 v53, 0
	v_mov_b32_e32 v54, 0
	v_mov_b32_e32 v55, 0
	v_mov_b32_e32 v56, 0
	v_mov_b32_e32 v57, 0
	v_mov_b32_e32 v58, 0
	v_mov_b32_e32 v59, 0
	v_mov_b32_e32 v60, 0
	v_mov_b32_e32 v61, 0
	v_mov_b32_e32 v62, 0
	v_mov_b32_e32 v63, 0
	v_mov_b32_e32 v64, 0
	v_mov_b32_e32 v65, 0
	v_mov_b32_e32 v2, 0
	v_mov_b32_e32 v3, 0
	v_mov_b32_e32 v4, 0
	v_mov_b32_e32 v5, 0
	v_mov_b32_e32 v6, 0
	v_mov_b32_e32 v7, 0
	v_mov_b32_e32 v8, 0
	v_mov_b32_e32 v9, 0
	v_mov_b32_e32 v10, 0
	v_mov_b32_e32 v11, 0
	v_mov_b32_e32 v12, 0
	v_mov_b32_e32 v13, 0
	v_mov_b32_e32 v14, 0
	v_mov_b32_e32 v15, 0
	v_mov_b32_e32 v16, 0
	v_mov_b32_e32 v17, 0
	v_mov_b32_e32 v18, 0
	v_mov_b32_e32 v19, 0
	v_mov_b32_e32 v20, 0
	v_mov_b32_e32 v21, 0
	v_mov_b32_e32 v22, 0
	v_mov_b32_e32 v23, 0
	v_mov_b32_e32 v24, 0
	v_mov_b32_e32 v25, 0
	v_mov_b32_e32 v26, 0
	v_mov_b32_e32 v27, 0
	v_mov_b32_e32 v28, 0
	v_mov_b32_e32 v29, 0
	v_mov_b32_e32 v30, 0
	v_mov_b32_e32 v31, 0
	v_mov_b32_e32 v32, 0
	v_mov_b32_e32 v33, 0
	v_mov_b32_e32 v94, 0
	v_mov_b32_e32 v95, 0
	v_mov_b32_e32 v96, 0
	v_mov_b32_e32 v97, 0
	v_mov_b32_e32 v98, 0
	v_mov_b32_e32 v99, 0
	v_mov_b32_e32 v100, 0
	v_mov_b32_e32 v101, 0
	v_mov_b32_e32 v102, 0
	v_mov_b32_e32 v103, 0
	v_mov_b32_e32 v104, 0
	v_mov_b32_e32 v105, 0
	v_mov_b32_e32 v106, 0
	v_mov_b32_e32 v107, 0
	v_mov_b32_e32 v108, 0
	v_mov_b32_e32 v109, 0
	v_mov_b32_e32 v110, 0
	v_mov_b32_e32 v111, 0
	v_mov_b32_e32 v112, 0
	v_mov_b32_e32 v113, 0
	v_mov_b32_e32 v114, 0
	v_mov_b32_e32 v115, 0
	v_mov_b32_e32 v116, 0
	v_mov_b32_e32 v117, 0
	v_mov_b32_e32 v118, 0
	v_mov_b32_e32 v119, 0
	v_mov_b32_e32 v120, 0
	v_mov_b32_e32 v121, 0
	v_mov_b32_e32 v122, 0
	v_mov_b32_e32 v123, 0
	v_mov_b32_e32 v124, 0
	v_mov_b32_e32 v125, 0
	v_mov_b32_e32 v134, 0
	v_mov_b32_e32 v135, 0
	v_mov_b32_e32 v136, 0
	v_mov_b32_e32 v137, 0
	v_mov_b32_e32 v138, 0
	v_mov_b32_e32 v139, 0
	v_mov_b32_e32 v140, 0
	v_mov_b32_e32 v141, 0
	v_mov_b32_e32 v142, 0
	v_mov_b32_e32 v143, 0
	v_mov_b32_e32 v144, 0
	v_mov_b32_e32 v145, 0
	v_mov_b32_e32 v146, 0
	v_mov_b32_e32 v147, 0
	v_mov_b32_e32 v148, 0
	v_mov_b32_e32 v149, 0
	v_mov_b32_e32 v150, 0
	v_mov_b32_e32 v151, 0
	v_mov_b32_e32 v152, 0
	v_mov_b32_e32 v153, 0
	v_mov_b32_e32 v154, 0
	v_mov_b32_e32 v155, 0
	v_mov_b32_e32 v156, 0
	v_mov_b32_e32 v157, 0
	v_mov_b32_e32 v158, 0
	v_mov_b32_e32 v159, 0
	v_mov_b32_e32 v160, 0
	v_mov_b32_e32 v161, 0
	v_mov_b32_e32 v162, 0
	v_mov_b32_e32 v163, 0
	v_mov_b32_e32 v164, 0
	v_mov_b32_e32 v165, 0
	s_barrier
	s_mov_b32 m0, vcc_lo
	s_nop 0
	global_load_lds_dwordx4 v[66:67], off
	s_add_u32 m0, vcc_lo, 0x6000
	s_nop 0
	global_load_lds_dwordx4 v[126:127], off
	s_add_u32 m0, vcc_lo, 0x400
	s_nop 0
	global_load_lds_dwordx4 v[68:69], off
	s_add_u32 m0, vcc_lo, 0x6400
	s_nop 0
	global_load_lds_dwordx4 v[128:129], off
	s_add_u32 m0, vcc_lo, 0x2000
	s_nop 0
	global_load_lds_dwordx4 v[70:71], off
	s_add_u32 m0, vcc_lo, 0x8000
	s_nop 0
	global_load_lds_dwordx4 v[130:131], off
	s_add_u32 m0, vcc_lo, 0x2400
	s_nop 0
	global_load_lds_dwordx4 v[72:73], off
	s_add_u32 m0, vcc_lo, 0x8400
	s_nop 0
	global_load_lds_dwordx4 v[132:133], off
	s_add_u32 m0, vcc_lo, 0x4000
	s_nop 0
	global_load_lds_dwordx4 v[74:75], off
	s_add_u32 m0, vcc_lo, 0xa000
	s_nop 0
	global_load_lds_dwordx4 v[244:245], off
	s_add_u32 m0, vcc_lo, 0x4400
	s_nop 0
	global_load_lds_dwordx4 v[76:77], off
	s_add_u32 m0, vcc_lo, 0xa400
	s_nop 0
	global_load_lds_dwordx4 v[246:247], off
	v_lshl_add_u64 v[66:67], v[66:67], 0, v[82:83]
	v_lshl_add_u64 v[68:69], v[68:69], 0, v[82:83]
	v_lshl_add_u64 v[70:71], v[70:71], 0, v[82:83]
	v_lshl_add_u64 v[72:73], v[72:73], 0, v[82:83]
	v_lshl_add_u64 v[74:75], v[74:75], 0, v[82:83]
	v_lshl_add_u64 v[76:77], v[76:77], 0, v[82:83]
	v_lshl_add_u64 v[126:127], v[126:127], 0, v[82:83]
	v_lshl_add_u64 v[128:129], v[128:129], 0, v[82:83]
	v_lshl_add_u64 v[130:131], v[130:131], 0, v[82:83]
	v_lshl_add_u64 v[132:133], v[132:133], 0, v[82:83]
	v_lshl_add_u64 v[244:245], v[244:245], 0, v[82:83]
	v_lshl_add_u64 v[246:247], v[246:247], 0, v[82:83]
	s_waitcnt vmcnt(0)
	s_barrier
	ds_read_b128 v[166:169], v78
	ds_read_b128 v[170:173], v80
	ds_read_b128 v[174:177], v80 offset:2048
	ds_read_b128 v[178:181], v78 offset:2048
	ds_read_b128 v[182:185], v78 offset:8192
	ds_read_b128 v[188:191], v78 offset:10240
	s_waitcnt lgkmcnt(4)
	v_mfma_f32_32x32x16_bf16 v[34:49], v[166:169], v[170:173], v[34:49]
	ds_read_b128 v[192:195], v79
	s_waitcnt lgkmcnt(4)
	v_mfma_f32_32x32x16_bf16 v[50:65], v[166:169], v[174:177], v[50:65]
	ds_read_b128 v[206:209], v81
	s_waitcnt lgkmcnt(4)
	v_mfma_f32_32x32x16_bf16 v[2:17], v[178:181], v[170:173], v[2:17]
	ds_read_b128 v[210:213], v81 offset:2048
	v_mfma_f32_32x32x16_bf16 v[18:33], v[178:181], v[174:177], v[18:33]
	ds_read_b128 v[222:225], v79 offset:2048
	s_waitcnt lgkmcnt(5)
	v_mfma_f32_32x32x16_bf16 v[94:109], v[182:185], v[170:173], v[94:109]
	ds_read_b128 v[236:239], v79 offset:8192
	v_mfma_f32_32x32x16_bf16 v[110:125], v[182:185], v[174:177], v[110:125]
	ds_read_b128 v[240:243], v79 offset:10240
	s_waitcnt lgkmcnt(6)
	v_mfma_f32_32x32x16_bf16 v[134:149], v[188:191], v[170:173], v[134:149]
	v_mfma_f32_32x32x16_bf16 v[150:165], v[188:191], v[174:177], v[150:165]
	s_waitcnt vmcnt(0) lgkmcnt(0)
	s_barrier
	s_mov_b32 vcc_hi, 4

.Lffp_next:
	s_cmpk_eq_u32 s81, 0x200
	s_cbranch_scc0 .Lffp_next_orig
	s_cmpk_lt_u32 s22, 0x200
	s_cbranch_scc1 .Lffp_add512
	s_cmpk_lt_u32 s22, 0x400
	s_cbranch_scc0 .Lffp_third
	s_cmpk_lt_u32 s22, 0x300
	s_cbranch_scc1 .Lffp_add512
	s_add_i32 s22, s22, 0x300
	s_branch .LBB0_192
.Lffp_third:
	s_cmpk_lt_u32 s22, 0x500
	s_cbranch_scc0 .Lffp_done
	s_add_i32 s22, s22, 0x100
	s_branch .LBB0_192
.Lffp_add512:
	s_add_i32 s22, s22, 0x200
	s_branch .LBB0_192

.Lffp_done:
	s_movk_i32 s96, 0x48
	s_mov_b32 s19, 0x80000
	s_mov_b32 s14, 0xdb629599
	s_mov_b32 s15, 0xf534ddc0
	s_mov_b32 s16, 0xfc2757d1
	s_mov_b64 s[12:13], s[30:31]
	v_readlane_b32 s22, v255, 2
	v_readlane_b32 s23, v255, 3
